# attention: top-n rank loops unrolled from registers (prompt), selected-block list compacted by a wave with ballot (sample)
# speedup vs baseline: 1.0123x; 1.0038x over previous
; __device__ __forceinline__ void attn_item(const P& p, Frame& F, const bool is_s, const int b, const int g, const int c) {
;     ...
;                 { const int q = tid2 >> 3, jg = tid2 & 7; const int tq = 64 * c + q;
; #pragma unroll
;                   for (int jj = 0; jj < 4; ++jj) { const int j = jg * 4 + jj; float v = ((IMP[(0 * 64 + q) * 33 + j] + IMP[(1 * 64 + q) * 33 + j]) + IMP[(2 * 64 + q) * 33 + j]) + IMP[(3 * 64 + q) * 33 + j];
;                       if (j == 0 || j == c || j == c - 1) v += 1e4f; if (j * 64 > tq) v = NEGB; IMP[q * 33 + j] = v; } }
;                 __syncthreads();
;                 { const int q = tid2 >> 3, jg = tid2 & 7; unsigned bits = 0u;
;                   for (int jj = 0; jj < 4; ++jj) { const int j = jg * 4 + jj; const float vj = IMP[q * 33 + j]; int rank = 0;
; #pragma nounroll
;                       for (int i = 0; i < 32; ++i) { const float vi = IMP[q * 33 + i]; rank += (vi > vj || (vi == vj && i < j)) ? 1 : 0; }
;                       if (rank < 16) bits |= 1u << j; }
.LBB0_1957:
	s_cmp_eq_u32 s5, 2
	s_cselect_b64 s[46:47], -1, 0
	s_cmp_lg_u32 s5, 2
	s_cselect_b64 s[42:43], -1, 0
	s_and_b64 vcc, exec, s[42:43]
	s_cbranch_vccnz .LBB0_2003
	v_mov_b32_e32 v9, v226
	s_mov_b64 s[0:1], -1
	s_and_b64 vcc, exec, s[56:57]
	s_waitcnt lgkmcnt(0)
	s_barrier
	s_cbranch_vccz .LBB0_1970
	v_ashrrev_i32_e32 v10, 3, v9
	v_readlane_b32 s0, v252, 44
	v_lshlrev_b32_e32 v1, 2, v9
	s_mov_b32 s14, s91
	v_add_u32_e32 v15, s0, v10
	s_movk_i32 s0, 0x84
	v_mul_lo_u32 v2, v10, s0
	v_readlane_b32 s0, v252, 14
	s_mov_b32 s15, s87
	s_mov_b32 s16, s90
	v_add_u32_e32 v11, s0, v2
	v_and_b32_e32 v2, 28, v1
	v_lshl_add_u32 v14, v2, 2, v11
	v_add_u32_e32 v16, 0x6300, v14
	v_add_u32_e32 v1, 0x2100, v14
	v_add_u32_e32 v8, 0x4200, v14
	ds_read2_b32 v[4:5], v14 offset1:1
	ds_read2_b32 v[6:7], v1 offset1:1
	ds_read2_b32 v[12:13], v8 offset1:1
	ds_read2_b32 v[16:17], v16 offset1:1
	v_cmp_eq_u32_e32 vcc, 0, v2
	v_cmp_eq_u32_e64 s[0:1], s14, v2
	s_waitcnt lgkmcnt(2)
	v_pk_add_f32 v[4:5], v[4:5], v[6:7]
	v_or_b32_e32 v1, 1, v2
	s_waitcnt lgkmcnt(1)
	v_pk_add_f32 v[4:5], v[4:5], v[12:13]
	s_or_b64 s[6:7], vcc, s[0:1]
	s_waitcnt lgkmcnt(0)
	v_pk_add_f32 v[4:5], v[4:5], v[16:17]
	v_cmp_eq_u32_e32 vcc, s14, v1
	v_cmp_eq_u32_e64 s[0:1], s15, v2
	v_cmp_eq_u32_e64 s[10:11], s16, v1
	s_mov_b32 s2, 0x461c4000
	v_pk_add_f32 v[6:7], v[4:5], s[2:3] op_sel_hi:[1,0]
	s_or_b64 s[0:1], s[6:7], s[0:1]
	s_or_b64 vcc, vcc, s[10:11]
	v_lshlrev_b32_e32 v1, 6, v1
	v_cndmask_b32_e64 v4, v4, v6, s[0:1]
	v_cndmask_b32_e32 v5, v5, v7, vcc
	v_lshlrev_b32_e32 v6, 6, v2
	v_cmp_le_i32_e32 vcc, v1, v15
	s_mov_b32 s6, 1
	s_mov_b32 s7, 0
	v_cndmask_b32_e32 v1, v222, v5, vcc
	v_cmp_le_i32_e32 vcc, v6, v15
	s_nop 1
	v_cndmask_b32_e32 v4, v222, v4, vcc
	ds_write2_b32 v14, v4, v1 offset1:1
	v_or_b32_e32 v4, 2, v2
	v_lshl_add_u32 v8, v4, 2, v11
	s_waitcnt vmcnt(0)
	v_add_u32_e32 v98, 0x6300, v8
	v_add_u32_e32 v1, 0x2100, v8
	v_add_u32_e32 v5, 0x4200, v8
	ds_read2_b32 v[6:7], v8 offset1:1
	ds_read2_b32 v[12:13], v1 offset1:1
	ds_read2_b32 v[16:17], v5 offset1:1
	ds_read2_b32 v[98:99], v98 offset1:1
	v_or_b32_e32 v1, 3, v2
	v_cmp_eq_u32_e32 vcc, s14, v4
	s_waitcnt lgkmcnt(2)
	v_pk_add_f32 v[6:7], v[6:7], v[12:13]
	v_cmp_eq_u32_e64 s[10:11], s15, v4
	s_waitcnt lgkmcnt(1)
	v_pk_add_f32 v[6:7], v[6:7], v[16:17]
	v_cmp_eq_u32_e64 s[0:1], s89, v1
	s_waitcnt lgkmcnt(0)
	v_pk_add_f32 v[6:7], v[6:7], v[98:99]
	v_cmp_eq_u32_e64 s[14:15], s16, v1
	v_pk_add_f32 v[12:13], v[6:7], s[2:3] op_sel_hi:[1,0]
	s_or_b64 vcc, vcc, s[10:11]
	v_cndmask_b32_e32 v5, v6, v12, vcc
	s_or_b64 vcc, s[0:1], s[14:15]
	v_lshlrev_b32_e32 v12, 6, v1
	v_cndmask_b32_e32 v6, v7, v13, vcc
	v_lshlrev_b32_e32 v7, 6, v4
	v_cmp_le_i32_e32 vcc, v12, v15
	s_mov_b32 s2, 0
	v_mov_b32_e32 v12, 0
	v_cndmask_b32_e32 v6, v222, v6, vcc
	v_cmp_le_i32_e32 vcc, v7, v15
	v_mov_b32_e32 v13, 0
	s_nop 0
	v_cndmask_b32_e32 v5, v222, v5, vcc
	ds_write2_b32 v8, v5, v6 offset1:1
	s_waitcnt lgkmcnt(0)
	s_barrier
	ds_read_b32 v6, v14
	ds_read2_b32 v[18:19], v11 offset0:0 offset1:1
	ds_read2_b32 v[20:21], v11 offset0:2 offset1:3
	ds_read2_b32 v[22:23], v11 offset0:4 offset1:5
	ds_read2_b32 v[24:25], v11 offset0:6 offset1:7
	ds_read2_b32 v[26:27], v11 offset0:8 offset1:9
	ds_read2_b32 v[28:29], v11 offset0:10 offset1:11
	ds_read2_b32 v[30:31], v11 offset0:12 offset1:13
	ds_read2_b32 v[32:33], v11 offset0:14 offset1:15
	s_waitcnt lgkmcnt(4)
	ds_read2_b32 v[34:35], v11 offset0:16 offset1:17
	ds_read2_b32 v[36:37], v11 offset0:18 offset1:19
	ds_read2_b32 v[38:39], v11 offset0:20 offset1:21
	ds_read2_b32 v[40:41], v11 offset0:22 offset1:23
	ds_read2_b32 v[42:43], v11 offset0:24 offset1:25
	ds_read2_b32 v[44:45], v11 offset0:26 offset1:27
	ds_read2_b32 v[46:47], v11 offset0:28 offset1:29
	ds_read2_b32 v[48:49], v11 offset0:30 offset1:31
	v_mov_b32_e32 v5, v2
	s_waitcnt lgkmcnt(0)
	v_mov_b32_e32 v7, v6
	v_cmp_lt_u32_e32 vcc, 0, v2
	v_cmp_lt_u32_e64 s[0:1], 1, v5
	v_cmp_eq_f32_e64 s[16:17], v18, v6
	v_cmp_eq_f32_e64 s[18:19], v19, v7
	v_cmp_gt_f32_e64 s[10:11], v19, v7
	v_cmp_gt_f32_e64 s[14:15], v18, v6
	s_and_b64 s[0:1], s[18:19], s[0:1]
	s_and_b64 s[16:17], s[16:17], vcc
	s_or_b64 vcc, s[14:15], s[16:17]
	s_or_b64 s[0:1], s[10:11], s[0:1]
	v_addc_co_u32_e64 v13, s[0:1], 0, v13, s[0:1]
	v_addc_co_u32_e32 v12, vcc, 0, v12, vcc
	v_cmp_lt_u32_e32 vcc, 2, v2
	v_cmp_lt_u32_e64 s[0:1], 3, v5
	v_cmp_eq_f32_e64 s[16:17], v20, v6
	v_cmp_eq_f32_e64 s[18:19], v21, v7
	v_cmp_gt_f32_e64 s[10:11], v21, v7
	v_cmp_gt_f32_e64 s[14:15], v20, v6
	s_and_b64 s[0:1], s[18:19], s[0:1]
	s_and_b64 s[16:17], s[16:17], vcc
	s_or_b64 vcc, s[14:15], s[16:17]
	s_or_b64 s[0:1], s[10:11], s[0:1]
	v_addc_co_u32_e64 v13, s[0:1], 0, v13, s[0:1]
	v_addc_co_u32_e32 v12, vcc, 0, v12, vcc
	v_cmp_lt_u32_e32 vcc, 4, v2
	v_cmp_lt_u32_e64 s[0:1], 5, v5
	v_cmp_eq_f32_e64 s[16:17], v22, v6
	v_cmp_eq_f32_e64 s[18:19], v23, v7
	v_cmp_gt_f32_e64 s[10:11], v23, v7
	v_cmp_gt_f32_e64 s[14:15], v22, v6
	s_and_b64 s[0:1], s[18:19], s[0:1]
	s_and_b64 s[16:17], s[16:17], vcc
	s_or_b64 vcc, s[14:15], s[16:17]
	s_or_b64 s[0:1], s[10:11], s[0:1]
	v_addc_co_u32_e64 v13, s[0:1], 0, v13, s[0:1]
	v_addc_co_u32_e32 v12, vcc, 0, v12, vcc
	v_cmp_lt_u32_e32 vcc, 6, v2
	v_cmp_lt_u32_e64 s[0:1], 7, v5
	v_cmp_eq_f32_e64 s[16:17], v24, v6
	v_cmp_eq_f32_e64 s[18:19], v25, v7
	v_cmp_gt_f32_e64 s[10:11], v25, v7
	v_cmp_gt_f32_e64 s[14:15], v24, v6
	s_and_b64 s[0:1], s[18:19], s[0:1]
	s_and_b64 s[16:17], s[16:17], vcc
	s_or_b64 vcc, s[14:15], s[16:17]
	s_or_b64 s[0:1], s[10:11], s[0:1]
	v_addc_co_u32_e64 v13, s[0:1], 0, v13, s[0:1]
	v_addc_co_u32_e32 v12, vcc, 0, v12, vcc
	v_cmp_lt_u32_e32 vcc, 8, v2
	v_cmp_lt_u32_e64 s[0:1], 9, v5
; __device__ __forceinline__ void attn_item(const P& p, Frame& F, const bool is_s, const int b, const int g, const int c) {
;     ...
;                 { const int q = tid2 >> 3, jg = tid2 & 7; unsigned bits = 0u;
;                   for (int jj = 0; jj < 4; ++jj) { const int j = jg * 4 + jj; const float vj = IMP[q * 33 + j]; int rank = 0;
; #pragma nounroll
;                       for (int i = 0; i < 32; ++i) { const float vi = IMP[q * 33 + i]; rank += (vi > vj || (vi == vj && i < j)) ? 1 : 0; }
;                       if (rank < 16) bits |= 1u << j; }
	v_cmp_eq_f32_e64 s[16:17], v26, v6
	v_cmp_eq_f32_e64 s[18:19], v27, v7
	v_cmp_gt_f32_e64 s[10:11], v27, v7
	v_cmp_gt_f32_e64 s[14:15], v26, v6
	s_and_b64 s[0:1], s[18:19], s[0:1]
	s_and_b64 s[16:17], s[16:17], vcc
	s_or_b64 vcc, s[14:15], s[16:17]
	s_or_b64 s[0:1], s[10:11], s[0:1]
	v_addc_co_u32_e64 v13, s[0:1], 0, v13, s[0:1]
	v_addc_co_u32_e32 v12, vcc, 0, v12, vcc
	v_cmp_lt_u32_e32 vcc, 10, v2
	v_cmp_lt_u32_e64 s[0:1], 11, v5
	v_cmp_eq_f32_e64 s[16:17], v28, v6
	v_cmp_eq_f32_e64 s[18:19], v29, v7
	v_cmp_gt_f32_e64 s[10:11], v29, v7
	v_cmp_gt_f32_e64 s[14:15], v28, v6
	s_and_b64 s[0:1], s[18:19], s[0:1]
	s_and_b64 s[16:17], s[16:17], vcc
	s_or_b64 vcc, s[14:15], s[16:17]
	s_or_b64 s[0:1], s[10:11], s[0:1]
	v_addc_co_u32_e64 v13, s[0:1], 0, v13, s[0:1]
	v_addc_co_u32_e32 v12, vcc, 0, v12, vcc
	v_cmp_lt_u32_e32 vcc, 12, v2
	v_cmp_lt_u32_e64 s[0:1], 13, v5
	v_cmp_eq_f32_e64 s[16:17], v30, v6
	v_cmp_eq_f32_e64 s[18:19], v31, v7
	v_cmp_gt_f32_e64 s[10:11], v31, v7
	v_cmp_gt_f32_e64 s[14:15], v30, v6
	s_and_b64 s[0:1], s[18:19], s[0:1]
	s_and_b64 s[16:17], s[16:17], vcc
	s_or_b64 vcc, s[14:15], s[16:17]
	s_or_b64 s[0:1], s[10:11], s[0:1]
	v_addc_co_u32_e64 v13, s[0:1], 0, v13, s[0:1]
	v_addc_co_u32_e32 v12, vcc, 0, v12, vcc
	v_cmp_lt_u32_e32 vcc, 14, v2
	v_cmp_lt_u32_e64 s[0:1], 15, v5
	v_cmp_eq_f32_e64 s[16:17], v32, v6
	v_cmp_eq_f32_e64 s[18:19], v33, v7
	v_cmp_gt_f32_e64 s[10:11], v33, v7
	v_cmp_gt_f32_e64 s[14:15], v32, v6
	s_and_b64 s[0:1], s[18:19], s[0:1]
	s_and_b64 s[16:17], s[16:17], vcc
	s_or_b64 vcc, s[14:15], s[16:17]
	s_or_b64 s[0:1], s[10:11], s[0:1]
	v_addc_co_u32_e64 v13, s[0:1], 0, v13, s[0:1]
	v_addc_co_u32_e32 v12, vcc, 0, v12, vcc
	v_cmp_lt_u32_e32 vcc, 16, v2
	v_cmp_lt_u32_e64 s[0:1], 17, v5
	v_cmp_eq_f32_e64 s[16:17], v34, v6
	v_cmp_eq_f32_e64 s[18:19], v35, v7
	v_cmp_gt_f32_e64 s[10:11], v35, v7
	v_cmp_gt_f32_e64 s[14:15], v34, v6
	s_and_b64 s[0:1], s[18:19], s[0:1]
	s_and_b64 s[16:17], s[16:17], vcc
	s_or_b64 vcc, s[14:15], s[16:17]
	s_or_b64 s[0:1], s[10:11], s[0:1]
	v_addc_co_u32_e64 v13, s[0:1], 0, v13, s[0:1]
	v_addc_co_u32_e32 v12, vcc, 0, v12, vcc
	v_cmp_lt_u32_e32 vcc, 18, v2
	v_cmp_lt_u32_e64 s[0:1], 19, v5
	v_cmp_eq_f32_e64 s[16:17], v36, v6
	v_cmp_eq_f32_e64 s[18:19], v37, v7
	v_cmp_gt_f32_e64 s[10:11], v37, v7
	v_cmp_gt_f32_e64 s[14:15], v36, v6
	s_and_b64 s[0:1], s[18:19], s[0:1]
	s_and_b64 s[16:17], s[16:17], vcc
	s_or_b64 vcc, s[14:15], s[16:17]
	s_or_b64 s[0:1], s[10:11], s[0:1]
	v_addc_co_u32_e64 v13, s[0:1], 0, v13, s[0:1]
	v_addc_co_u32_e32 v12, vcc, 0, v12, vcc
	v_cmp_lt_u32_e32 vcc, 20, v2
	v_cmp_lt_u32_e64 s[0:1], 21, v5
	v_cmp_eq_f32_e64 s[16:17], v38, v6
	v_cmp_eq_f32_e64 s[18:19], v39, v7
	v_cmp_gt_f32_e64 s[10:11], v39, v7
	v_cmp_gt_f32_e64 s[14:15], v38, v6
	s_and_b64 s[0:1], s[18:19], s[0:1]
	s_and_b64 s[16:17], s[16:17], vcc
	s_or_b64 vcc, s[14:15], s[16:17]
	s_or_b64 s[0:1], s[10:11], s[0:1]
	v_addc_co_u32_e64 v13, s[0:1], 0, v13, s[0:1]
	v_addc_co_u32_e32 v12, vcc, 0, v12, vcc
	v_cmp_lt_u32_e32 vcc, 22, v2
	v_cmp_lt_u32_e64 s[0:1], 23, v5
	v_cmp_eq_f32_e64 s[16:17], v40, v6
	v_cmp_eq_f32_e64 s[18:19], v41, v7
	v_cmp_gt_f32_e64 s[10:11], v41, v7
	v_cmp_gt_f32_e64 s[14:15], v40, v6
	s_and_b64 s[0:1], s[18:19], s[0:1]
	s_and_b64 s[16:17], s[16:17], vcc
	s_or_b64 vcc, s[14:15], s[16:17]
	s_or_b64 s[0:1], s[10:11], s[0:1]
	v_addc_co_u32_e64 v13, s[0:1], 0, v13, s[0:1]
	v_addc_co_u32_e32 v12, vcc, 0, v12, vcc
	v_cmp_lt_u32_e32 vcc, 24, v2
	v_cmp_lt_u32_e64 s[0:1], 25, v5
	v_cmp_eq_f32_e64 s[16:17], v42, v6
	v_cmp_eq_f32_e64 s[18:19], v43, v7
	v_cmp_gt_f32_e64 s[10:11], v43, v7
	v_cmp_gt_f32_e64 s[14:15], v42, v6
	s_and_b64 s[0:1], s[18:19], s[0:1]
	s_and_b64 s[16:17], s[16:17], vcc
	s_or_b64 vcc, s[14:15], s[16:17]
	s_or_b64 s[0:1], s[10:11], s[0:1]
	v_addc_co_u32_e64 v13, s[0:1], 0, v13, s[0:1]
	v_addc_co_u32_e32 v12, vcc, 0, v12, vcc
	v_cmp_lt_u32_e32 vcc, 26, v2
	v_cmp_lt_u32_e64 s[0:1], 27, v5
	v_cmp_eq_f32_e64 s[16:17], v44, v6
	v_cmp_eq_f32_e64 s[18:19], v45, v7
	v_cmp_gt_f32_e64 s[10:11], v45, v7
	v_cmp_gt_f32_e64 s[14:15], v44, v6
	s_and_b64 s[0:1], s[18:19], s[0:1]
	s_and_b64 s[16:17], s[16:17], vcc
	s_or_b64 vcc, s[14:15], s[16:17]
	s_or_b64 s[0:1], s[10:11], s[0:1]
	v_addc_co_u32_e64 v13, s[0:1], 0, v13, s[0:1]
	v_addc_co_u32_e32 v12, vcc, 0, v12, vcc
	v_cmp_lt_u32_e32 vcc, 28, v2
	v_cmp_lt_u32_e64 s[0:1], 29, v5
	v_cmp_eq_f32_e64 s[16:17], v46, v6
	v_cmp_eq_f32_e64 s[18:19], v47, v7
	v_cmp_gt_f32_e64 s[10:11], v47, v7
	v_cmp_gt_f32_e64 s[14:15], v46, v6
	s_and_b64 s[0:1], s[18:19], s[0:1]
	s_and_b64 s[16:17], s[16:17], vcc
	s_or_b64 vcc, s[14:15], s[16:17]
	s_or_b64 s[0:1], s[10:11], s[0:1]
	v_addc_co_u32_e64 v13, s[0:1], 0, v13, s[0:1]
	v_addc_co_u32_e32 v12, vcc, 0, v12, vcc
	v_cmp_lt_u32_e32 vcc, 30, v2
	v_cmp_lt_u32_e64 s[0:1], 31, v5
	v_cmp_eq_f32_e64 s[16:17], v48, v6
	v_cmp_eq_f32_e64 s[18:19], v49, v7
	v_cmp_gt_f32_e64 s[10:11], v49, v7
	v_cmp_gt_f32_e64 s[14:15], v48, v6
	s_and_b64 s[0:1], s[18:19], s[0:1]
	s_and_b64 s[16:17], s[16:17], vcc
	s_or_b64 vcc, s[14:15], s[16:17]
	s_or_b64 s[0:1], s[10:11], s[0:1]
	v_addc_co_u32_e64 v13, s[0:1], 0, v13, s[0:1]
	v_addc_co_u32_e32 v12, vcc, 0, v12, vcc
	ds_read_b32 v6, v14 offset:4
	s_mov_b32 s2, 1
	s_mov_b32 s6, 0
	v_mov_b32_e32 v14, 0
	v_mov_b32_e32 v15, 0
	s_waitcnt lgkmcnt(0)
; __device__ __forceinline__ void attn_item(const P& p, Frame& F, const bool is_s, const int b, const int g, const int c) {
;     ...
;                 { const int q = tid2 >> 3, jg = tid2 & 7; unsigned bits = 0u;
;                   for (int jj = 0; jj < 4; ++jj) { const int j = jg * 4 + jj; const float vj = IMP[q * 33 + j]; int rank = 0;
; #pragma nounroll
;                       for (int i = 0; i < 32; ++i) { const float vi = IMP[q * 33 + i]; rank += (vi > vj || (vi == vj && i < j)) ? 1 : 0; }
;                       if (rank < 16) bits |= 1u << j; }
	v_mov_b32_e32 v7, v6
	s_mov_b32 s7, 0
	v_cmp_le_u32_e32 vcc, 0, v2
	v_cmp_le_u32_e64 s[0:1], 1, v5
	v_cmp_eq_f32_e64 s[16:17], v18, v6
	v_cmp_eq_f32_e64 s[18:19], v19, v7
	v_cmp_gt_f32_e64 s[10:11], v19, v7
	v_cmp_gt_f32_e64 s[14:15], v18, v6
	s_and_b64 s[0:1], s[18:19], s[0:1]
	s_and_b64 s[16:17], s[16:17], vcc
	s_or_b64 vcc, s[14:15], s[16:17]
	s_or_b64 s[0:1], s[10:11], s[0:1]
	v_addc_co_u32_e64 v15, s[0:1], 0, v15, s[0:1]
	v_addc_co_u32_e32 v14, vcc, 0, v14, vcc
	v_cmp_le_u32_e32 vcc, 2, v2
	v_cmp_le_u32_e64 s[0:1], 3, v5
	v_cmp_eq_f32_e64 s[16:17], v20, v6
	v_cmp_eq_f32_e64 s[18:19], v21, v7
	v_cmp_gt_f32_e64 s[10:11], v21, v7
	v_cmp_gt_f32_e64 s[14:15], v20, v6
	s_and_b64 s[0:1], s[18:19], s[0:1]
	s_and_b64 s[16:17], s[16:17], vcc
	s_or_b64 vcc, s[14:15], s[16:17]
	s_or_b64 s[0:1], s[10:11], s[0:1]
	v_addc_co_u32_e64 v15, s[0:1], 0, v15, s[0:1]
	v_addc_co_u32_e32 v14, vcc, 0, v14, vcc
	v_cmp_le_u32_e32 vcc, 4, v2
	v_cmp_le_u32_e64 s[0:1], 5, v5
	v_cmp_eq_f32_e64 s[16:17], v22, v6
	v_cmp_eq_f32_e64 s[18:19], v23, v7
	v_cmp_gt_f32_e64 s[10:11], v23, v7
	v_cmp_gt_f32_e64 s[14:15], v22, v6
	s_and_b64 s[0:1], s[18:19], s[0:1]
	s_and_b64 s[16:17], s[16:17], vcc
	s_or_b64 vcc, s[14:15], s[16:17]
	s_or_b64 s[0:1], s[10:11], s[0:1]
	v_addc_co_u32_e64 v15, s[0:1], 0, v15, s[0:1]
	v_addc_co_u32_e32 v14, vcc, 0, v14, vcc
	v_cmp_le_u32_e32 vcc, 6, v2
	v_cmp_le_u32_e64 s[0:1], 7, v5
	v_cmp_eq_f32_e64 s[16:17], v24, v6
	v_cmp_eq_f32_e64 s[18:19], v25, v7
	v_cmp_gt_f32_e64 s[10:11], v25, v7
	v_cmp_gt_f32_e64 s[14:15], v24, v6
	s_and_b64 s[0:1], s[18:19], s[0:1]
	s_and_b64 s[16:17], s[16:17], vcc
	s_or_b64 vcc, s[14:15], s[16:17]
	s_or_b64 s[0:1], s[10:11], s[0:1]
	v_addc_co_u32_e64 v15, s[0:1], 0, v15, s[0:1]
	v_addc_co_u32_e32 v14, vcc, 0, v14, vcc
	v_cmp_le_u32_e32 vcc, 8, v2
	v_cmp_le_u32_e64 s[0:1], 9, v5
	v_cmp_eq_f32_e64 s[16:17], v26, v6
	v_cmp_eq_f32_e64 s[18:19], v27, v7
	v_cmp_gt_f32_e64 s[10:11], v27, v7
	v_cmp_gt_f32_e64 s[14:15], v26, v6
	s_and_b64 s[0:1], s[18:19], s[0:1]
	s_and_b64 s[16:17], s[16:17], vcc
	s_or_b64 vcc, s[14:15], s[16:17]
	s_or_b64 s[0:1], s[10:11], s[0:1]
	v_addc_co_u32_e64 v15, s[0:1], 0, v15, s[0:1]
	v_addc_co_u32_e32 v14, vcc, 0, v14, vcc
	v_cmp_le_u32_e32 vcc, 10, v2
	v_cmp_le_u32_e64 s[0:1], 11, v5
	v_cmp_eq_f32_e64 s[16:17], v28, v6
	v_cmp_eq_f32_e64 s[18:19], v29, v7
	v_cmp_gt_f32_e64 s[10:11], v29, v7
	v_cmp_gt_f32_e64 s[14:15], v28, v6
	s_and_b64 s[0:1], s[18:19], s[0:1]
	s_and_b64 s[16:17], s[16:17], vcc
	s_or_b64 vcc, s[14:15], s[16:17]
	s_or_b64 s[0:1], s[10:11], s[0:1]
	v_addc_co_u32_e64 v15, s[0:1], 0, v15, s[0:1]
	v_addc_co_u32_e32 v14, vcc, 0, v14, vcc
	v_cmp_le_u32_e32 vcc, 12, v2
	v_cmp_le_u32_e64 s[0:1], 13, v5
	v_cmp_eq_f32_e64 s[16:17], v30, v6
	v_cmp_eq_f32_e64 s[18:19], v31, v7
	v_cmp_gt_f32_e64 s[10:11], v31, v7
	v_cmp_gt_f32_e64 s[14:15], v30, v6
	s_and_b64 s[0:1], s[18:19], s[0:1]
	s_and_b64 s[16:17], s[16:17], vcc
	s_or_b64 vcc, s[14:15], s[16:17]
	s_or_b64 s[0:1], s[10:11], s[0:1]
	v_addc_co_u32_e64 v15, s[0:1], 0, v15, s[0:1]
	v_addc_co_u32_e32 v14, vcc, 0, v14, vcc
	v_cmp_le_u32_e32 vcc, 14, v2
	v_cmp_le_u32_e64 s[0:1], 15, v5
	v_cmp_eq_f32_e64 s[16:17], v32, v6
	v_cmp_eq_f32_e64 s[18:19], v33, v7
	v_cmp_gt_f32_e64 s[10:11], v33, v7
	v_cmp_gt_f32_e64 s[14:15], v32, v6
	s_and_b64 s[0:1], s[18:19], s[0:1]
	s_and_b64 s[16:17], s[16:17], vcc
	s_or_b64 vcc, s[14:15], s[16:17]
	s_or_b64 s[0:1], s[10:11], s[0:1]
	v_addc_co_u32_e64 v15, s[0:1], 0, v15, s[0:1]
	v_addc_co_u32_e32 v14, vcc, 0, v14, vcc
	v_cmp_le_u32_e32 vcc, 16, v2
	v_cmp_le_u32_e64 s[0:1], 17, v5
	v_cmp_eq_f32_e64 s[16:17], v34, v6
	v_cmp_eq_f32_e64 s[18:19], v35, v7
	v_cmp_gt_f32_e64 s[10:11], v35, v7
	v_cmp_gt_f32_e64 s[14:15], v34, v6
	s_and_b64 s[0:1], s[18:19], s[0:1]
	s_and_b64 s[16:17], s[16:17], vcc
	s_or_b64 vcc, s[14:15], s[16:17]
	s_or_b64 s[0:1], s[10:11], s[0:1]
	v_addc_co_u32_e64 v15, s[0:1], 0, v15, s[0:1]
	v_addc_co_u32_e32 v14, vcc, 0, v14, vcc
	v_cmp_le_u32_e32 vcc, 18, v2
	v_cmp_le_u32_e64 s[0:1], 19, v5
	v_cmp_eq_f32_e64 s[16:17], v36, v6
	v_cmp_eq_f32_e64 s[18:19], v37, v7
	v_cmp_gt_f32_e64 s[10:11], v37, v7
	v_cmp_gt_f32_e64 s[14:15], v36, v6
	s_and_b64 s[0:1], s[18:19], s[0:1]
	s_and_b64 s[16:17], s[16:17], vcc
	s_or_b64 vcc, s[14:15], s[16:17]
	s_or_b64 s[0:1], s[10:11], s[0:1]
	v_addc_co_u32_e64 v15, s[0:1], 0, v15, s[0:1]
	v_addc_co_u32_e32 v14, vcc, 0, v14, vcc
	v_cmp_le_u32_e32 vcc, 20, v2
	v_cmp_le_u32_e64 s[0:1], 21, v5
	v_cmp_eq_f32_e64 s[16:17], v38, v6
	v_cmp_eq_f32_e64 s[18:19], v39, v7
	v_cmp_gt_f32_e64 s[10:11], v39, v7
	v_cmp_gt_f32_e64 s[14:15], v38, v6
	s_and_b64 s[0:1], s[18:19], s[0:1]
	s_and_b64 s[16:17], s[16:17], vcc
	s_or_b64 vcc, s[14:15], s[16:17]
	s_or_b64 s[0:1], s[10:11], s[0:1]
	v_addc_co_u32_e64 v15, s[0:1], 0, v15, s[0:1]
	v_addc_co_u32_e32 v14, vcc, 0, v14, vcc
	v_cmp_le_u32_e32 vcc, 22, v2
	v_cmp_le_u32_e64 s[0:1], 23, v5
	v_cmp_eq_f32_e64 s[16:17], v40, v6
	v_cmp_eq_f32_e64 s[18:19], v41, v7
	v_cmp_gt_f32_e64 s[10:11], v41, v7
	v_cmp_gt_f32_e64 s[14:15], v40, v6
	s_and_b64 s[0:1], s[18:19], s[0:1]
	s_and_b64 s[16:17], s[16:17], vcc
	s_or_b64 vcc, s[14:15], s[16:17]
	s_or_b64 s[0:1], s[10:11], s[0:1]
	v_addc_co_u32_e64 v15, s[0:1], 0, v15, s[0:1]
	v_addc_co_u32_e32 v14, vcc, 0, v14, vcc
	v_cmp_le_u32_e32 vcc, 24, v2
	v_cmp_le_u32_e64 s[0:1], 25, v5
	v_cmp_eq_f32_e64 s[16:17], v42, v6
	v_cmp_eq_f32_e64 s[18:19], v43, v7
	v_cmp_gt_f32_e64 s[10:11], v43, v7
	v_cmp_gt_f32_e64 s[14:15], v42, v6
	s_and_b64 s[0:1], s[18:19], s[0:1]
	s_and_b64 s[16:17], s[16:17], vcc
	s_or_b64 vcc, s[14:15], s[16:17]
	s_or_b64 s[0:1], s[10:11], s[0:1]
	v_addc_co_u32_e64 v15, s[0:1], 0, v15, s[0:1]
; __device__ __forceinline__ void attn_item(const P& p, Frame& F, const bool is_s, const int b, const int g, const int c) {
;     ...
;                 { const int q = tid2 >> 3, jg = tid2 & 7; unsigned bits = 0u;
;                   for (int jj = 0; jj < 4; ++jj) { const int j = jg * 4 + jj; const float vj = IMP[q * 33 + j]; int rank = 0;
; #pragma nounroll
;                       for (int i = 0; i < 32; ++i) { const float vi = IMP[q * 33 + i]; rank += (vi > vj || (vi == vj && i < j)) ? 1 : 0; }
;                       if (rank < 16) bits |= 1u << j; }
	v_addc_co_u32_e32 v14, vcc, 0, v14, vcc
	v_cmp_le_u32_e32 vcc, 26, v2
	v_cmp_le_u32_e64 s[0:1], 27, v5
	v_cmp_eq_f32_e64 s[16:17], v44, v6
	v_cmp_eq_f32_e64 s[18:19], v45, v7
	v_cmp_gt_f32_e64 s[10:11], v45, v7
	v_cmp_gt_f32_e64 s[14:15], v44, v6
	s_and_b64 s[0:1], s[18:19], s[0:1]
	s_and_b64 s[16:17], s[16:17], vcc
	s_or_b64 vcc, s[14:15], s[16:17]
	s_or_b64 s[0:1], s[10:11], s[0:1]
	v_addc_co_u32_e64 v15, s[0:1], 0, v15, s[0:1]
	v_addc_co_u32_e32 v14, vcc, 0, v14, vcc
	v_cmp_le_u32_e32 vcc, 28, v2
	v_cmp_le_u32_e64 s[0:1], 29, v5
	v_cmp_eq_f32_e64 s[16:17], v46, v6
	v_cmp_eq_f32_e64 s[18:19], v47, v7
	v_cmp_gt_f32_e64 s[10:11], v47, v7
	v_cmp_gt_f32_e64 s[14:15], v46, v6
	s_and_b64 s[0:1], s[18:19], s[0:1]
	s_and_b64 s[16:17], s[16:17], vcc
	s_or_b64 vcc, s[14:15], s[16:17]
	s_or_b64 s[0:1], s[10:11], s[0:1]
	v_addc_co_u32_e64 v15, s[0:1], 0, v15, s[0:1]
	v_addc_co_u32_e32 v14, vcc, 0, v14, vcc
	v_cmp_le_u32_e32 vcc, 30, v2
	v_cmp_le_u32_e64 s[0:1], 31, v5
	v_cmp_eq_f32_e64 s[16:17], v48, v6
	v_cmp_eq_f32_e64 s[18:19], v49, v7
	v_cmp_gt_f32_e64 s[10:11], v49, v7
	v_cmp_gt_f32_e64 s[14:15], v48, v6
	s_and_b64 s[0:1], s[18:19], s[0:1]
	s_and_b64 s[16:17], s[16:17], vcc
	s_or_b64 vcc, s[14:15], s[16:17]
	s_or_b64 s[0:1], s[10:11], s[0:1]
	v_addc_co_u32_e64 v15, s[0:1], 0, v15, s[0:1]
	v_addc_co_u32_e32 v14, vcc, 0, v14, vcc
	ds_read_b32 v6, v8
	v_mov_b32_e32 v8, v4
	v_mov_b32_e32 v5, v4
	s_mov_b32 s2, 1
	s_mov_b32 s6, 0
	s_waitcnt lgkmcnt(0)
	v_mov_b32_e32 v7, v6
	v_mov_b32_e32 v16, 0
	v_mov_b32_e32 v17, 0
	s_mov_b32 s7, 0
	v_cmp_lt_u32_e32 vcc, 0, v8
	v_cmp_lt_u32_e64 s[0:1], 1, v5
	v_cmp_eq_f32_e64 s[16:17], v18, v6
	v_cmp_eq_f32_e64 s[18:19], v19, v7
	v_cmp_gt_f32_e64 s[10:11], v19, v7
	v_cmp_gt_f32_e64 s[14:15], v18, v6
	s_and_b64 s[0:1], s[18:19], s[0:1]
	s_and_b64 s[16:17], s[16:17], vcc
	s_or_b64 vcc, s[14:15], s[16:17]
	s_or_b64 s[0:1], s[10:11], s[0:1]
	v_addc_co_u32_e64 v17, s[0:1], 0, v17, s[0:1]
	v_addc_co_u32_e32 v16, vcc, 0, v16, vcc
	v_cmp_lt_u32_e32 vcc, 2, v8
	v_cmp_lt_u32_e64 s[0:1], 3, v5
	v_cmp_eq_f32_e64 s[16:17], v20, v6
	v_cmp_eq_f32_e64 s[18:19], v21, v7
	v_cmp_gt_f32_e64 s[10:11], v21, v7
	v_cmp_gt_f32_e64 s[14:15], v20, v6
	s_and_b64 s[0:1], s[18:19], s[0:1]
	s_and_b64 s[16:17], s[16:17], vcc
	s_or_b64 vcc, s[14:15], s[16:17]
	s_or_b64 s[0:1], s[10:11], s[0:1]
	v_addc_co_u32_e64 v17, s[0:1], 0, v17, s[0:1]
	v_addc_co_u32_e32 v16, vcc, 0, v16, vcc
	v_cmp_lt_u32_e32 vcc, 4, v8
	v_cmp_lt_u32_e64 s[0:1], 5, v5
	v_cmp_eq_f32_e64 s[16:17], v22, v6
	v_cmp_eq_f32_e64 s[18:19], v23, v7
	v_cmp_gt_f32_e64 s[10:11], v23, v7
	v_cmp_gt_f32_e64 s[14:15], v22, v6
	s_and_b64 s[0:1], s[18:19], s[0:1]
	s_and_b64 s[16:17], s[16:17], vcc
	s_or_b64 vcc, s[14:15], s[16:17]
	s_or_b64 s[0:1], s[10:11], s[0:1]
	v_addc_co_u32_e64 v17, s[0:1], 0, v17, s[0:1]
	v_addc_co_u32_e32 v16, vcc, 0, v16, vcc
	v_cmp_lt_u32_e32 vcc, 6, v8
	v_cmp_lt_u32_e64 s[0:1], 7, v5
	v_cmp_eq_f32_e64 s[16:17], v24, v6
	v_cmp_eq_f32_e64 s[18:19], v25, v7
	v_cmp_gt_f32_e64 s[10:11], v25, v7
	v_cmp_gt_f32_e64 s[14:15], v24, v6
	s_and_b64 s[0:1], s[18:19], s[0:1]
	s_and_b64 s[16:17], s[16:17], vcc
	s_or_b64 vcc, s[14:15], s[16:17]
	s_or_b64 s[0:1], s[10:11], s[0:1]
	v_addc_co_u32_e64 v17, s[0:1], 0, v17, s[0:1]
	v_addc_co_u32_e32 v16, vcc, 0, v16, vcc
	v_cmp_lt_u32_e32 vcc, 8, v8
	v_cmp_lt_u32_e64 s[0:1], 9, v5
	v_cmp_eq_f32_e64 s[16:17], v26, v6
	v_cmp_eq_f32_e64 s[18:19], v27, v7
	v_cmp_gt_f32_e64 s[10:11], v27, v7
	v_cmp_gt_f32_e64 s[14:15], v26, v6
	s_and_b64 s[0:1], s[18:19], s[0:1]
	s_and_b64 s[16:17], s[16:17], vcc
	s_or_b64 vcc, s[14:15], s[16:17]
	s_or_b64 s[0:1], s[10:11], s[0:1]
	v_addc_co_u32_e64 v17, s[0:1], 0, v17, s[0:1]
	v_addc_co_u32_e32 v16, vcc, 0, v16, vcc
	v_cmp_lt_u32_e32 vcc, 10, v8
	v_cmp_lt_u32_e64 s[0:1], 11, v5
	v_cmp_eq_f32_e64 s[16:17], v28, v6
	v_cmp_eq_f32_e64 s[18:19], v29, v7
	v_cmp_gt_f32_e64 s[10:11], v29, v7
	v_cmp_gt_f32_e64 s[14:15], v28, v6
	s_and_b64 s[0:1], s[18:19], s[0:1]
	s_and_b64 s[16:17], s[16:17], vcc
	s_or_b64 vcc, s[14:15], s[16:17]
	s_or_b64 s[0:1], s[10:11], s[0:1]
	v_addc_co_u32_e64 v17, s[0:1], 0, v17, s[0:1]
	v_addc_co_u32_e32 v16, vcc, 0, v16, vcc
	v_cmp_lt_u32_e32 vcc, 12, v8
	v_cmp_lt_u32_e64 s[0:1], 13, v5
	v_cmp_eq_f32_e64 s[16:17], v30, v6
	v_cmp_eq_f32_e64 s[18:19], v31, v7
	v_cmp_gt_f32_e64 s[10:11], v31, v7
	v_cmp_gt_f32_e64 s[14:15], v30, v6
	s_and_b64 s[0:1], s[18:19], s[0:1]
	s_and_b64 s[16:17], s[16:17], vcc
	s_or_b64 vcc, s[14:15], s[16:17]
	s_or_b64 s[0:1], s[10:11], s[0:1]
	v_addc_co_u32_e64 v17, s[0:1], 0, v17, s[0:1]
	v_addc_co_u32_e32 v16, vcc, 0, v16, vcc
	v_cmp_lt_u32_e32 vcc, 14, v8
	v_cmp_lt_u32_e64 s[0:1], 15, v5
	v_cmp_eq_f32_e64 s[16:17], v32, v6
	v_cmp_eq_f32_e64 s[18:19], v33, v7
	v_cmp_gt_f32_e64 s[10:11], v33, v7
	v_cmp_gt_f32_e64 s[14:15], v32, v6
	s_and_b64 s[0:1], s[18:19], s[0:1]
	s_and_b64 s[16:17], s[16:17], vcc
	s_or_b64 vcc, s[14:15], s[16:17]
	s_or_b64 s[0:1], s[10:11], s[0:1]
	v_addc_co_u32_e64 v17, s[0:1], 0, v17, s[0:1]
	v_addc_co_u32_e32 v16, vcc, 0, v16, vcc
	v_cmp_lt_u32_e32 vcc, 16, v8
	v_cmp_lt_u32_e64 s[0:1], 17, v5
	v_cmp_eq_f32_e64 s[16:17], v34, v6
	v_cmp_eq_f32_e64 s[18:19], v35, v7
	v_cmp_gt_f32_e64 s[10:11], v35, v7
	v_cmp_gt_f32_e64 s[14:15], v34, v6
	s_and_b64 s[0:1], s[18:19], s[0:1]
	s_and_b64 s[16:17], s[16:17], vcc
	s_or_b64 vcc, s[14:15], s[16:17]
	s_or_b64 s[0:1], s[10:11], s[0:1]
	v_addc_co_u32_e64 v17, s[0:1], 0, v17, s[0:1]
	v_addc_co_u32_e32 v16, vcc, 0, v16, vcc
	v_cmp_lt_u32_e32 vcc, 18, v8
	v_cmp_lt_u32_e64 s[0:1], 19, v5
	v_cmp_eq_f32_e64 s[16:17], v36, v6
	v_cmp_eq_f32_e64 s[18:19], v37, v7
	v_cmp_gt_f32_e64 s[10:11], v37, v7
; __device__ __forceinline__ void attn_item(const P& p, Frame& F, const bool is_s, const int b, const int g, const int c) {
;     ...
;                 { const int q = tid2 >> 3, jg = tid2 & 7; unsigned bits = 0u;
;                   for (int jj = 0; jj < 4; ++jj) { const int j = jg * 4 + jj; const float vj = IMP[q * 33 + j]; int rank = 0;
; #pragma nounroll
;                       for (int i = 0; i < 32; ++i) { const float vi = IMP[q * 33 + i]; rank += (vi > vj || (vi == vj && i < j)) ? 1 : 0; }
;                       if (rank < 16) bits |= 1u << j; }
	v_cmp_gt_f32_e64 s[14:15], v36, v6
	s_and_b64 s[0:1], s[18:19], s[0:1]
	s_and_b64 s[16:17], s[16:17], vcc
	s_or_b64 vcc, s[14:15], s[16:17]
	s_or_b64 s[0:1], s[10:11], s[0:1]
	v_addc_co_u32_e64 v17, s[0:1], 0, v17, s[0:1]
	v_addc_co_u32_e32 v16, vcc, 0, v16, vcc
	v_cmp_lt_u32_e32 vcc, 20, v8
	v_cmp_lt_u32_e64 s[0:1], 21, v5
	v_cmp_eq_f32_e64 s[16:17], v38, v6
	v_cmp_eq_f32_e64 s[18:19], v39, v7
	v_cmp_gt_f32_e64 s[10:11], v39, v7
	v_cmp_gt_f32_e64 s[14:15], v38, v6
	s_and_b64 s[0:1], s[18:19], s[0:1]
	s_and_b64 s[16:17], s[16:17], vcc
	s_or_b64 vcc, s[14:15], s[16:17]
	s_or_b64 s[0:1], s[10:11], s[0:1]
	v_addc_co_u32_e64 v17, s[0:1], 0, v17, s[0:1]
	v_addc_co_u32_e32 v16, vcc, 0, v16, vcc
	v_cmp_lt_u32_e32 vcc, 22, v8
	v_cmp_lt_u32_e64 s[0:1], 23, v5
	v_cmp_eq_f32_e64 s[16:17], v40, v6
	v_cmp_eq_f32_e64 s[18:19], v41, v7
	v_cmp_gt_f32_e64 s[10:11], v41, v7
	v_cmp_gt_f32_e64 s[14:15], v40, v6
	s_and_b64 s[0:1], s[18:19], s[0:1]
	s_and_b64 s[16:17], s[16:17], vcc
	s_or_b64 vcc, s[14:15], s[16:17]
	s_or_b64 s[0:1], s[10:11], s[0:1]
	v_addc_co_u32_e64 v17, s[0:1], 0, v17, s[0:1]
	v_addc_co_u32_e32 v16, vcc, 0, v16, vcc
	v_cmp_lt_u32_e32 vcc, 24, v8
	v_cmp_lt_u32_e64 s[0:1], 25, v5
	v_cmp_eq_f32_e64 s[16:17], v42, v6
	v_cmp_eq_f32_e64 s[18:19], v43, v7
	v_cmp_gt_f32_e64 s[10:11], v43, v7
	v_cmp_gt_f32_e64 s[14:15], v42, v6
	s_and_b64 s[0:1], s[18:19], s[0:1]
	s_and_b64 s[16:17], s[16:17], vcc
	s_or_b64 vcc, s[14:15], s[16:17]
	s_or_b64 s[0:1], s[10:11], s[0:1]
	v_addc_co_u32_e64 v17, s[0:1], 0, v17, s[0:1]
	v_addc_co_u32_e32 v16, vcc, 0, v16, vcc
	v_cmp_lt_u32_e32 vcc, 26, v8
	v_cmp_lt_u32_e64 s[0:1], 27, v5
	v_cmp_eq_f32_e64 s[16:17], v44, v6
	v_cmp_eq_f32_e64 s[18:19], v45, v7
	v_cmp_gt_f32_e64 s[10:11], v45, v7
	v_cmp_gt_f32_e64 s[14:15], v44, v6
	s_and_b64 s[0:1], s[18:19], s[0:1]
	s_and_b64 s[16:17], s[16:17], vcc
	s_or_b64 vcc, s[14:15], s[16:17]
	s_or_b64 s[0:1], s[10:11], s[0:1]
	v_addc_co_u32_e64 v17, s[0:1], 0, v17, s[0:1]
	v_addc_co_u32_e32 v16, vcc, 0, v16, vcc
	v_cmp_lt_u32_e32 vcc, 28, v8
	v_cmp_lt_u32_e64 s[0:1], 29, v5
	v_cmp_eq_f32_e64 s[16:17], v46, v6
	v_cmp_eq_f32_e64 s[18:19], v47, v7
	v_cmp_gt_f32_e64 s[10:11], v47, v7
	v_cmp_gt_f32_e64 s[14:15], v46, v6
	s_and_b64 s[0:1], s[18:19], s[0:1]
	s_and_b64 s[16:17], s[16:17], vcc
	s_or_b64 vcc, s[14:15], s[16:17]
	s_or_b64 s[0:1], s[10:11], s[0:1]
	v_addc_co_u32_e64 v17, s[0:1], 0, v17, s[0:1]
	v_addc_co_u32_e32 v16, vcc, 0, v16, vcc
	v_cmp_lt_u32_e32 vcc, 30, v8
	v_cmp_lt_u32_e64 s[0:1], 31, v5
	v_cmp_eq_f32_e64 s[16:17], v48, v6
	v_cmp_eq_f32_e64 s[18:19], v49, v7
	v_cmp_gt_f32_e64 s[10:11], v49, v7
	v_cmp_gt_f32_e64 s[14:15], v48, v6
	s_and_b64 s[0:1], s[18:19], s[0:1]
	s_and_b64 s[16:17], s[16:17], vcc
	s_or_b64 vcc, s[14:15], s[16:17]
	s_or_b64 s[0:1], s[10:11], s[0:1]
	v_addc_co_u32_e64 v17, s[0:1], 0, v17, s[0:1]
	v_addc_co_u32_e32 v16, vcc, 0, v16, vcc
	v_lshl_add_u32 v4, v1, 2, v11
	ds_read_b32 v4, v4
	v_mov_b32_e32 v6, v1
	s_mov_b32 s2, 1
	s_mov_b32 s6, 0
	v_mov_b32_e32 v7, 0
	s_waitcnt lgkmcnt(0)
	v_mov_b32_e32 v5, v4
	v_mov_b32_e32 v8, 0
	s_mov_b32 s7, 0
	v_cmp_lt_u32_e32 vcc, 0, v6
	v_cmp_lt_u32_e64 s[0:1], 1, v1
	v_cmp_eq_f32_e64 s[16:17], v18, v4
	v_cmp_eq_f32_e64 s[18:19], v19, v5
	v_cmp_gt_f32_e64 s[10:11], v19, v5
	v_cmp_gt_f32_e64 s[14:15], v18, v4
	s_and_b64 s[0:1], s[18:19], s[0:1]
	s_and_b64 s[16:17], s[16:17], vcc
	s_or_b64 vcc, s[14:15], s[16:17]
	s_or_b64 s[0:1], s[10:11], s[0:1]
	v_addc_co_u32_e64 v8, s[0:1], 0, v8, s[0:1]
	v_addc_co_u32_e32 v7, vcc, 0, v7, vcc
	v_cmp_lt_u32_e32 vcc, 2, v6
	v_cmp_lt_u32_e64 s[0:1], 3, v1
	v_cmp_eq_f32_e64 s[16:17], v20, v4
	v_cmp_eq_f32_e64 s[18:19], v21, v5
	v_cmp_gt_f32_e64 s[10:11], v21, v5
	v_cmp_gt_f32_e64 s[14:15], v20, v4
	s_and_b64 s[0:1], s[18:19], s[0:1]
	s_and_b64 s[16:17], s[16:17], vcc
	s_or_b64 vcc, s[14:15], s[16:17]
	s_or_b64 s[0:1], s[10:11], s[0:1]
	v_addc_co_u32_e64 v8, s[0:1], 0, v8, s[0:1]
	v_addc_co_u32_e32 v7, vcc, 0, v7, vcc
	v_cmp_lt_u32_e32 vcc, 4, v6
	v_cmp_lt_u32_e64 s[0:1], 5, v1
	v_cmp_eq_f32_e64 s[16:17], v22, v4
	v_cmp_eq_f32_e64 s[18:19], v23, v5
	v_cmp_gt_f32_e64 s[10:11], v23, v5
	v_cmp_gt_f32_e64 s[14:15], v22, v4
	s_and_b64 s[0:1], s[18:19], s[0:1]
	s_and_b64 s[16:17], s[16:17], vcc
	s_or_b64 vcc, s[14:15], s[16:17]
	s_or_b64 s[0:1], s[10:11], s[0:1]
	v_addc_co_u32_e64 v8, s[0:1], 0, v8, s[0:1]
	v_addc_co_u32_e32 v7, vcc, 0, v7, vcc
	v_cmp_lt_u32_e32 vcc, 6, v6
	v_cmp_lt_u32_e64 s[0:1], 7, v1
	v_cmp_eq_f32_e64 s[16:17], v24, v4
	v_cmp_eq_f32_e64 s[18:19], v25, v5
	v_cmp_gt_f32_e64 s[10:11], v25, v5
	v_cmp_gt_f32_e64 s[14:15], v24, v4
	s_and_b64 s[0:1], s[18:19], s[0:1]
	s_and_b64 s[16:17], s[16:17], vcc
	s_or_b64 vcc, s[14:15], s[16:17]
	s_or_b64 s[0:1], s[10:11], s[0:1]
	v_addc_co_u32_e64 v8, s[0:1], 0, v8, s[0:1]
	v_addc_co_u32_e32 v7, vcc, 0, v7, vcc
	v_cmp_lt_u32_e32 vcc, 8, v6
	v_cmp_lt_u32_e64 s[0:1], 9, v1
	v_cmp_eq_f32_e64 s[16:17], v26, v4
	v_cmp_eq_f32_e64 s[18:19], v27, v5
	v_cmp_gt_f32_e64 s[10:11], v27, v5
	v_cmp_gt_f32_e64 s[14:15], v26, v4
	s_and_b64 s[0:1], s[18:19], s[0:1]
	s_and_b64 s[16:17], s[16:17], vcc
	s_or_b64 vcc, s[14:15], s[16:17]
	s_or_b64 s[0:1], s[10:11], s[0:1]
	v_addc_co_u32_e64 v8, s[0:1], 0, v8, s[0:1]
	v_addc_co_u32_e32 v7, vcc, 0, v7, vcc
	v_cmp_lt_u32_e32 vcc, 10, v6
	v_cmp_lt_u32_e64 s[0:1], 11, v1
	v_cmp_eq_f32_e64 s[16:17], v28, v4
	v_cmp_eq_f32_e64 s[18:19], v29, v5
	v_cmp_gt_f32_e64 s[10:11], v29, v5
; __device__ __forceinline__ void attn_item(const P& p, Frame& F, const bool is_s, const int b, const int g, const int c) {
;     ...
;                 { const int q = tid2 >> 3, jg = tid2 & 7; unsigned bits = 0u;
;                   for (int jj = 0; jj < 4; ++jj) { const int j = jg * 4 + jj; const float vj = IMP[q * 33 + j]; int rank = 0;
; #pragma nounroll
;                       for (int i = 0; i < 32; ++i) { const float vi = IMP[q * 33 + i]; rank += (vi > vj || (vi == vj && i < j)) ? 1 : 0; }
;                       if (rank < 16) bits |= 1u << j; }
;                   if (bits) atomicOr((unsigned*)&SELM[q], bits); }
;                 __syncthreads();
;                 selm = SELM[iq];
	v_cmp_gt_f32_e64 s[14:15], v28, v4
	s_and_b64 s[0:1], s[18:19], s[0:1]
	s_and_b64 s[16:17], s[16:17], vcc
	s_or_b64 vcc, s[14:15], s[16:17]
	s_or_b64 s[0:1], s[10:11], s[0:1]
	v_addc_co_u32_e64 v8, s[0:1], 0, v8, s[0:1]
	v_addc_co_u32_e32 v7, vcc, 0, v7, vcc
	v_cmp_lt_u32_e32 vcc, 12, v6
	v_cmp_lt_u32_e64 s[0:1], 13, v1
	v_cmp_eq_f32_e64 s[16:17], v30, v4
	v_cmp_eq_f32_e64 s[18:19], v31, v5
	v_cmp_gt_f32_e64 s[10:11], v31, v5
	v_cmp_gt_f32_e64 s[14:15], v30, v4
	s_and_b64 s[0:1], s[18:19], s[0:1]
	s_and_b64 s[16:17], s[16:17], vcc
	s_or_b64 vcc, s[14:15], s[16:17]
	s_or_b64 s[0:1], s[10:11], s[0:1]
	v_addc_co_u32_e64 v8, s[0:1], 0, v8, s[0:1]
	v_addc_co_u32_e32 v7, vcc, 0, v7, vcc
	v_cmp_lt_u32_e32 vcc, 14, v6
	v_cmp_lt_u32_e64 s[0:1], 15, v1
	v_cmp_eq_f32_e64 s[16:17], v32, v4
	v_cmp_eq_f32_e64 s[18:19], v33, v5
	v_cmp_gt_f32_e64 s[10:11], v33, v5
	v_cmp_gt_f32_e64 s[14:15], v32, v4
	s_and_b64 s[0:1], s[18:19], s[0:1]
	s_and_b64 s[16:17], s[16:17], vcc
	s_or_b64 vcc, s[14:15], s[16:17]
	s_or_b64 s[0:1], s[10:11], s[0:1]
	v_addc_co_u32_e64 v8, s[0:1], 0, v8, s[0:1]
	v_addc_co_u32_e32 v7, vcc, 0, v7, vcc
	v_cmp_lt_u32_e32 vcc, 16, v6
	v_cmp_lt_u32_e64 s[0:1], 17, v1
	v_cmp_eq_f32_e64 s[16:17], v34, v4
	v_cmp_eq_f32_e64 s[18:19], v35, v5
	v_cmp_gt_f32_e64 s[10:11], v35, v5
	v_cmp_gt_f32_e64 s[14:15], v34, v4
	s_and_b64 s[0:1], s[18:19], s[0:1]
	s_and_b64 s[16:17], s[16:17], vcc
	s_or_b64 vcc, s[14:15], s[16:17]
	s_or_b64 s[0:1], s[10:11], s[0:1]
	v_addc_co_u32_e64 v8, s[0:1], 0, v8, s[0:1]
	v_addc_co_u32_e32 v7, vcc, 0, v7, vcc
	v_cmp_lt_u32_e32 vcc, 18, v6
	v_cmp_lt_u32_e64 s[0:1], 19, v1
	v_cmp_eq_f32_e64 s[16:17], v36, v4
	v_cmp_eq_f32_e64 s[18:19], v37, v5
	v_cmp_gt_f32_e64 s[10:11], v37, v5
	v_cmp_gt_f32_e64 s[14:15], v36, v4
	s_and_b64 s[0:1], s[18:19], s[0:1]
	s_and_b64 s[16:17], s[16:17], vcc
	s_or_b64 vcc, s[14:15], s[16:17]
	s_or_b64 s[0:1], s[10:11], s[0:1]
	v_addc_co_u32_e64 v8, s[0:1], 0, v8, s[0:1]
	v_addc_co_u32_e32 v7, vcc, 0, v7, vcc
	v_cmp_lt_u32_e32 vcc, 20, v6
	v_cmp_lt_u32_e64 s[0:1], 21, v1
	v_cmp_eq_f32_e64 s[16:17], v38, v4
	v_cmp_eq_f32_e64 s[18:19], v39, v5
	v_cmp_gt_f32_e64 s[10:11], v39, v5
	v_cmp_gt_f32_e64 s[14:15], v38, v4
	s_and_b64 s[0:1], s[18:19], s[0:1]
	s_and_b64 s[16:17], s[16:17], vcc
	s_or_b64 vcc, s[14:15], s[16:17]
	s_or_b64 s[0:1], s[10:11], s[0:1]
	v_addc_co_u32_e64 v8, s[0:1], 0, v8, s[0:1]
	v_addc_co_u32_e32 v7, vcc, 0, v7, vcc
	v_cmp_lt_u32_e32 vcc, 22, v6
	v_cmp_lt_u32_e64 s[0:1], 23, v1
	v_cmp_eq_f32_e64 s[16:17], v40, v4
	v_cmp_eq_f32_e64 s[18:19], v41, v5
	v_cmp_gt_f32_e64 s[10:11], v41, v5
	v_cmp_gt_f32_e64 s[14:15], v40, v4
	s_and_b64 s[0:1], s[18:19], s[0:1]
	s_and_b64 s[16:17], s[16:17], vcc
	s_or_b64 vcc, s[14:15], s[16:17]
	s_or_b64 s[0:1], s[10:11], s[0:1]
	v_addc_co_u32_e64 v8, s[0:1], 0, v8, s[0:1]
	v_addc_co_u32_e32 v7, vcc, 0, v7, vcc
	v_cmp_lt_u32_e32 vcc, 24, v6
	v_cmp_lt_u32_e64 s[0:1], 25, v1
	v_cmp_eq_f32_e64 s[16:17], v42, v4
	v_cmp_eq_f32_e64 s[18:19], v43, v5
	v_cmp_gt_f32_e64 s[10:11], v43, v5
	v_cmp_gt_f32_e64 s[14:15], v42, v4
	s_and_b64 s[0:1], s[18:19], s[0:1]
	s_and_b64 s[16:17], s[16:17], vcc
	s_or_b64 vcc, s[14:15], s[16:17]
	s_or_b64 s[0:1], s[10:11], s[0:1]
	v_addc_co_u32_e64 v8, s[0:1], 0, v8, s[0:1]
	v_addc_co_u32_e32 v7, vcc, 0, v7, vcc
	v_cmp_lt_u32_e32 vcc, 26, v6
	v_cmp_lt_u32_e64 s[0:1], 27, v1
	v_cmp_eq_f32_e64 s[16:17], v44, v4
	v_cmp_eq_f32_e64 s[18:19], v45, v5
	v_cmp_gt_f32_e64 s[10:11], v45, v5
	v_cmp_gt_f32_e64 s[14:15], v44, v4
	s_and_b64 s[0:1], s[18:19], s[0:1]
	s_and_b64 s[16:17], s[16:17], vcc
	s_or_b64 vcc, s[14:15], s[16:17]
	s_or_b64 s[0:1], s[10:11], s[0:1]
	v_addc_co_u32_e64 v8, s[0:1], 0, v8, s[0:1]
	v_addc_co_u32_e32 v7, vcc, 0, v7, vcc
	v_cmp_lt_u32_e32 vcc, 28, v6
	v_cmp_lt_u32_e64 s[0:1], 29, v1
	v_cmp_eq_f32_e64 s[16:17], v46, v4
	v_cmp_eq_f32_e64 s[18:19], v47, v5
	v_cmp_gt_f32_e64 s[10:11], v47, v5
	v_cmp_gt_f32_e64 s[14:15], v46, v4
	s_and_b64 s[0:1], s[18:19], s[0:1]
	s_and_b64 s[16:17], s[16:17], vcc
	s_or_b64 vcc, s[14:15], s[16:17]
	s_or_b64 s[0:1], s[10:11], s[0:1]
	v_addc_co_u32_e64 v8, s[0:1], 0, v8, s[0:1]
	v_addc_co_u32_e32 v7, vcc, 0, v7, vcc
	v_cmp_lt_u32_e32 vcc, 30, v6
	v_cmp_lt_u32_e64 s[0:1], 31, v1
	v_cmp_eq_f32_e64 s[16:17], v48, v4
	v_cmp_eq_f32_e64 s[18:19], v49, v5
	v_cmp_gt_f32_e64 s[10:11], v49, v5
	v_cmp_gt_f32_e64 s[14:15], v48, v4
	s_and_b64 s[0:1], s[18:19], s[0:1]
	s_and_b64 s[16:17], s[16:17], vcc
	s_or_b64 vcc, s[14:15], s[16:17]
	s_or_b64 s[0:1], s[10:11], s[0:1]
	v_addc_co_u32_e64 v8, s[0:1], 0, v8, s[0:1]
	v_addc_co_u32_e32 v7, vcc, 0, v7, vcc
	v_add_u32_e32 v1, v12, v13
	v_add_u32_e32 v4, v14, v15
	v_lshlrev_b32_e64 v5, v2, 1
	v_cmp_gt_u32_e32 vcc, 16, v1
	v_add_u32_e32 v6, v16, v17
	s_nop 0
	v_cndmask_b32_e32 v1, 0, v5, vcc
	v_lshlrev_b32_e64 v5, v2, 2
	v_cmp_gt_u32_e32 vcc, 16, v4
	s_nop 1
	v_cndmask_b32_e32 v4, 0, v5, vcc
	v_or_b32_e32 v1, v4, v1
	v_lshlrev_b32_e64 v4, v2, 4
	v_add_u32_e32 v5, v7, v8
	v_cmp_gt_u32_e32 vcc, 16, v6
	v_lshlrev_b32_e64 v2, v2, 8
	s_nop 0
	v_cndmask_b32_e32 v4, 0, v4, vcc
	v_cmp_gt_u32_e32 vcc, 16, v5
	s_nop 1
	v_cndmask_b32_e32 v2, 0, v2, vcc
	v_or3_b32 v1, v1, v4, v2
	v_cmp_ne_u32_e32 vcc, 0, v1
	s_and_saveexec_b64 s[0:1], vcc
	v_lshl_add_u32 v2, v10, 2, 0
	v_add_u32_e32 v2, 0x19000, v2
	ds_or_b32 v2, v1
	s_or_b64 exec, exec, s[0:1]
	s_waitcnt lgkmcnt(0)
	s_barrier
	ds_read_b32 v1, v231
	s_mov_b64 s[0:1], 0

; __device__ __forceinline__ void attn_item(const P& p, Frame& F, const bool is_s, const int b, const int g, const int c) {
;     ...
;                 if (tid2 == 0) { int n = 0; for (int j = 0; j < 129; ++j) { const int msk = SELB[j] | (SELB[132 + j] << 1) | (SELB[264 + j] << 2) | (SELB[396 + j] << 3); if (msk) { UL[n] = j; UM[n] = msk; ++n; } } NU[0] = n; }
;                 __syncthreads();
;                 nu = NU[0];
.LBB0_1991:
	s_or_b64 exec, exec, s[0:1]
	v_cmp_eq_u32_e32 vcc, 0, v9
	s_waitcnt lgkmcnt(0)
	s_barrier
	s_mov_b64 s[0:1], exec
	v_readfirstlane_b32 s2, v9
	s_mov_b32 s7, 0
	s_nop 2
	s_cmp_lt_u32 s2, 64
	s_cbranch_scc0 .LBB0_2001
	v_mov_b32_e32 v8, 0x19600
	v_lshl_add_u32 v1, v9, 2, v8
	v_mov_b32_e32 v2, v9
	ds_read_b32 v4, v1
	ds_read_b32 v5, v1 offset:528
	ds_read_b32 v6, v1 offset:1056
	ds_read_b32 v7, v1 offset:1584
	s_waitcnt lgkmcnt(0)
	v_lshl_or_b32 v4, v5, 1, v4
	v_lshl_or_b32 v4, v6, 2, v4
	v_lshl_or_b32 v4, v7, 3, v4
	v_cmp_ne_u32_e64 s[10:11], 0, v4
	s_nop 1
	v_mbcnt_lo_u32_b32 v5, s10, 0
	v_mbcnt_hi_u32_b32 v5, s11, v5
	v_add_u32_e32 v5, s7, v5
	v_lshlrev_b32_e32 v5, 2, v5
	v_add_u32_e32 v5, 0x19100, v5
	s_bcnt1_i32_b64 s2, s[10:11]
	s_add_i32 s7, s7, s2
	s_and_b64 exec, exec, s[10:11]
	ds_write_b32 v5, v2
	ds_write_b32 v5, v4 offset:512
	s_mov_b64 exec, s[0:1]
	v_add_u32_e32 v2, 64, v9
	v_lshl_add_u32 v1, v2, 2, v8
	ds_read_b32 v4, v1
	ds_read_b32 v5, v1 offset:528
	ds_read_b32 v6, v1 offset:1056
	ds_read_b32 v7, v1 offset:1584
	s_waitcnt lgkmcnt(0)
	v_lshl_or_b32 v4, v5, 1, v4
	v_lshl_or_b32 v4, v6, 2, v4
	v_lshl_or_b32 v4, v7, 3, v4
	v_cmp_ne_u32_e64 s[10:11], 0, v4
	s_nop 1
	v_mbcnt_lo_u32_b32 v5, s10, 0
	v_mbcnt_hi_u32_b32 v5, s11, v5
	v_add_u32_e32 v5, s7, v5
	v_lshlrev_b32_e32 v5, 2, v5
	v_add_u32_e32 v5, 0x19100, v5
	s_bcnt1_i32_b64 s2, s[10:11]
	s_add_i32 s7, s7, s2
	s_and_b64 exec, exec, s[10:11]
	ds_write_b32 v5, v2
	ds_write_b32 v5, v4 offset:512
	s_mov_b64 exec, s[0:1]
	v_add_u32_e32 v2, 128, v9
	v_lshl_add_u32 v1, v2, 2, v8
	v_cmp_gt_u32_e32 vcc, 129, v2
	s_and_b64 exec, exec, vcc
	ds_read_b32 v4, v1
	ds_read_b32 v5, v1 offset:528
	ds_read_b32 v6, v1 offset:1056
	ds_read_b32 v7, v1 offset:1584
	s_waitcnt lgkmcnt(0)
	v_lshl_or_b32 v4, v5, 1, v4
	v_lshl_or_b32 v4, v6, 2, v4
	v_lshl_or_b32 v4, v7, 3, v4
	v_cmp_ne_u32_e64 s[10:11], 0, v4
	s_nop 1
	v_mbcnt_lo_u32_b32 v5, s10, 0
	v_mbcnt_hi_u32_b32 v5, s11, v5
	v_add_u32_e32 v5, s7, v5
	v_lshlrev_b32_e32 v5, 2, v5
	v_add_u32_e32 v5, 0x19100, v5
	s_bcnt1_i32_b64 s2, s[10:11]
	s_add_i32 s7, s7, s2
	s_and_b64 exec, exec, s[10:11]
	ds_write_b32 v5, v2
	ds_write_b32 v5, v4 offset:512
	s_mov_b64 exec, s[0:1]
	v_mov_b32_e32 v1, 0x19500
	v_mov_b32_e32 v2, s7
	ds_write_b32 v1, v2
